# barrier v3 plus: the halfway arriver of each XCC issues an early unwaited L2 write-back so the leader's final write-back finds less dirty data
# speedup vs baseline: 1.0500x; 1.0066x over previous
.Lcen_done:
	v_min_u32_e32 v2, 1, v2
	v_min_u32_e32 v3, 1, v3
	v_min_u32_e32 v4, 1, v4
	v_min_u32_e32 v5, 1, v5
	v_min_u32_e32 v6, 1, v6
	v_min_u32_e32 v7, 1, v7
	v_min_u32_e32 v8, 1, v8
	v_min_u32_e32 v9, 1, v9
	v_add_u32_e32 v1, v2, v3
	v_add_u32_e32 v1, v1, v4
	v_add_u32_e32 v1, v1, v5
	v_add_u32_e32 v1, v1, v6
	v_add_u32_e32 v1, v1, v7
	v_add_u32_e32 v1, v1, v8
	v_add_u32_e32 v1, v1, v9
	s_nop 0
	v_readfirstlane_b32 s101, v1
	s_getreg_b32 s5, hwreg(HW_REG_XCC_ID, 0, 4)
	s_lshl_b32 s5, s5, 8
	s_add_u32 s5, s5, 0x1000
	v_mov_b32_e32 v0, s5
	global_load_dword v1, v0, s[68:69] sc1
	s_waitcnt vmcnt(0)
	v_readfirstlane_b32 s98, v1
	s_nop 3
	s_sub_i32 s4, 1, s34
	s_getreg_b32 s5, hwreg(HW_REG_XCC_ID, 0, 4)
	s_mul_i32 s6, s98, s4
	s_lshl_b32 s5, s5, 8
	v_mov_b32_e32 v0, s5
	v_mov_b32_e32 v1, 1
	global_atomic_add v1, v0, v1, s[68:69] sc0
	s_mul_i32 s4, s101, s4
	v_mov_b32_e32 v0, 0
	s_waitcnt vmcnt(0)
	v_add_u32_e32 v1, 1, v1
	v_cmp_eq_u32_e32 vcc, s6, v1
	s_cbranch_vccz .Lgb_half_s0
	buffer_wbl2 sc1
	s_waitcnt vmcnt(0)
	v_mov_b32_e32 v1, 1
	global_atomic_add v0, v1, s[14:15]
	s_branch .Lgb_inv_s0
.Lgb_half_s0:
	s_lshr_b32 s7, s98, 1
	s_sub_u32 s7, s6, s7
	v_cmp_eq_u32_e32 vcc, s7, v1
	s_cbranch_vccz .Lgb_inv_s0
	buffer_wbl2 sc1

.LBB0_151:
	s_cmp_lt_i32 s35, 3
	s_cbranch_scc1 .LBB0_160
	v_mbcnt_lo_u32_b32 v0, -1, 0
	v_mbcnt_hi_u32_b32 v0, -1, v0
	s_waitcnt vmcnt(0) lgkmcnt(0)
	s_waitcnt vmcnt(0) lgkmcnt(0)
	v_add_u32_e32 v0, s84, v0
	v_cmp_gt_u32_e32 vcc, 64, v0
	s_barrier
	s_and_saveexec_b64 s[0:1], vcc
	s_cbranch_execz .LBB0_159
	s_waitcnt vmcnt(0)
	v_cmp_eq_u32_e32 vcc, 0, v0
	s_and_saveexec_b64 s[2:3], vcc
	s_cbranch_execz .LBB0_158
	s_sub_i32 s4, 2, s34
	s_getreg_b32 s5, hwreg(HW_REG_XCC_ID, 0, 4)
	s_mul_i32 s6, s98, s4
	s_lshl_b32 s5, s5, 8
	v_mov_b32_e32 v0, s5
	v_mov_b32_e32 v1, 1
	global_atomic_add v1, v0, v1, s[68:69] sc0
	s_mul_i32 s4, s101, s4
	v_mov_b32_e32 v0, 0
	s_waitcnt vmcnt(0)
	v_add_u32_e32 v1, 1, v1
	v_cmp_eq_u32_e32 vcc, s6, v1
	s_cbranch_vccz .Lgb_half_s1
	buffer_wbl2 sc1
	s_waitcnt vmcnt(0)
	v_mov_b32_e32 v1, 1
	global_atomic_add v0, v1, s[14:15]
	s_branch .Lgb_inv_s1

.LBB0_211:
	s_cmp_eq_u32 s100, 1
	s_cbranch_scc1 .Ldil_ret12
	s_cmp_lt_i32 s35, 4
	s_cbranch_scc1 .LBB0_220
	v_mbcnt_lo_u32_b32 v0, -1, 0
	v_mbcnt_hi_u32_b32 v0, -1, v0
	s_waitcnt vmcnt(0) lgkmcnt(0)
	s_waitcnt lgkmcnt(0)
	v_add_u32_e32 v0, s84, v0
	v_cmp_gt_u32_e32 vcc, 64, v0
	s_barrier
	s_and_saveexec_b64 s[0:1], vcc
	s_cbranch_execz .LBB0_219
	s_waitcnt vmcnt(0)
	s_waitcnt vmcnt(0)
	v_cmp_eq_u32_e32 vcc, 0, v0
	s_and_saveexec_b64 s[2:3], vcc
	s_cbranch_execz .LBB0_218
	s_sub_i32 s4, 3, s34
	s_getreg_b32 s5, hwreg(HW_REG_XCC_ID, 0, 4)
	s_mul_i32 s6, s98, s4
	s_lshl_b32 s5, s5, 8
	v_mov_b32_e32 v0, s5
	v_mov_b32_e32 v1, 1
	global_atomic_add v1, v0, v1, s[68:69] sc0
	s_mul_i32 s4, s101, s4
	v_mov_b32_e32 v0, 0
	s_waitcnt vmcnt(0)
	v_add_u32_e32 v1, 1, v1
	v_cmp_eq_u32_e32 vcc, s6, v1
	s_cbranch_vccz .Lgb_half_s2
	buffer_wbl2 sc1
	s_waitcnt vmcnt(0)
	v_mov_b32_e32 v1, 1
	global_atomic_add v0, v1, s[14:15]
	s_branch .Lgb_inv_s2

.LBB0_245:
	s_cmp_lt_i32 s35, 5
	s_cbranch_scc1 .LBB0_254
	v_mbcnt_lo_u32_b32 v0, -1, 0
	v_mbcnt_hi_u32_b32 v0, -1, v0
	s_waitcnt vmcnt(0) lgkmcnt(0)
	s_waitcnt vmcnt(0) lgkmcnt(0)
	v_add_u32_e32 v0, s84, v0
	v_cmp_gt_u32_e32 vcc, 64, v0
	s_barrier
	s_and_saveexec_b64 s[0:1], vcc
	s_cbranch_execz .LBB0_253
	s_waitcnt vmcnt(0)
	v_cmp_eq_u32_e32 vcc, 0, v0
	s_and_saveexec_b64 s[2:3], vcc
	s_cbranch_execz .LBB0_252
	s_sub_i32 s4, 4, s34
	s_getreg_b32 s5, hwreg(HW_REG_XCC_ID, 0, 4)
	s_mul_i32 s6, s98, s4
	s_lshl_b32 s5, s5, 8
	v_mov_b32_e32 v0, s5
	v_mov_b32_e32 v1, 1
	global_atomic_add v1, v0, v1, s[68:69] sc0
	s_mul_i32 s4, s101, s4
	v_mov_b32_e32 v0, 0
	s_waitcnt vmcnt(0)
	v_add_u32_e32 v1, 1, v1
	v_cmp_eq_u32_e32 vcc, s6, v1
	s_cbranch_vccz .Lgb_half_s3
	buffer_wbl2 sc1
	s_waitcnt vmcnt(0)
	v_mov_b32_e32 v1, 1
	global_atomic_add v0, v1, s[14:15]
	s_branch .Lgb_inv_s3

.LBB0_289:
	s_cmp_eq_u32 s99, 1
	s_cbranch_scc1 .Lmla_ret14
	s_cmp_lt_i32 s35, 6
	s_cbranch_scc1 .LBB0_298
	v_mbcnt_lo_u32_b32 v0, -1, 0
	v_mbcnt_hi_u32_b32 v0, -1, v0
	s_waitcnt vmcnt(0) lgkmcnt(0)
	s_waitcnt lgkmcnt(0)
	v_add_u32_e32 v0, s84, v0
	v_cmp_gt_u32_e32 vcc, 64, v0
	s_barrier
	s_and_saveexec_b64 s[0:1], vcc
	s_cbranch_execz .LBB0_297
	s_waitcnt vmcnt(0)
	s_waitcnt vmcnt(0)
	v_cmp_eq_u32_e32 vcc, 0, v0
	s_and_saveexec_b64 s[2:3], vcc
	s_cbranch_execz .LBB0_296
	s_sub_i32 s4, 5, s34
	s_getreg_b32 s5, hwreg(HW_REG_XCC_ID, 0, 4)
	s_mul_i32 s6, s98, s4
	s_lshl_b32 s5, s5, 8
	v_mov_b32_e32 v0, s5
	v_mov_b32_e32 v1, 1
	global_atomic_add v1, v0, v1, s[68:69] sc0
	s_mul_i32 s4, s101, s4
	v_mov_b32_e32 v0, 0
	s_waitcnt vmcnt(0)
	v_add_u32_e32 v1, 1, v1
	v_cmp_eq_u32_e32 vcc, s6, v1
	s_cbranch_vccz .Lgb_half_s4
	buffer_wbl2 sc1
	s_waitcnt vmcnt(0)
	v_mov_b32_e32 v1, 1
	global_atomic_add v0, v1, s[14:15]
	s_branch .Lgb_inv_s4

.LBB0_302:
	s_or_b64 exec, exec, s[2:3]
	s_cmp_lt_u32 s35, 7
	s_cbranch_scc1 .LBB0_311
	v_mbcnt_lo_u32_b32 v0, -1, 0
	v_mbcnt_hi_u32_b32 v0, -1, v0
	s_waitcnt vmcnt(0) lgkmcnt(0)
	s_waitcnt lgkmcnt(0)
	v_add_u32_e32 v0, s84, v0
	v_cmp_gt_u32_e32 vcc, 64, v0
	s_barrier
	s_and_saveexec_b64 s[0:1], vcc
	s_cbranch_execz .LBB0_310
	s_waitcnt vmcnt(0)
	s_waitcnt vmcnt(0)
	v_cmp_eq_u32_e32 vcc, 0, v0
	s_and_saveexec_b64 s[2:3], vcc
	s_cbranch_execz .LBB0_309
	s_sub_i32 s4, 6, s34
	s_getreg_b32 s5, hwreg(HW_REG_XCC_ID, 0, 4)
	s_mul_i32 s6, s98, s4
	s_lshl_b32 s5, s5, 8
	v_mov_b32_e32 v0, s5
	v_mov_b32_e32 v1, 1
	global_atomic_add v1, v0, v1, s[68:69] sc0
	s_mul_i32 s4, s101, s4
	v_mov_b32_e32 v0, 0
	s_waitcnt vmcnt(0)
	v_add_u32_e32 v1, 1, v1
	v_cmp_eq_u32_e32 vcc, s6, v1
	s_cbranch_vccz .Lgb_half_s5
	buffer_wbl2 sc1
	s_waitcnt vmcnt(0)
	v_mov_b32_e32 v1, 1
	global_atomic_add v0, v1, s[14:15]
	s_branch .Lgb_inv_s5

.LBB0_327:
	s_cmp_lt_i32 s35, 8
	s_cbranch_scc1 .LBB0_336
	v_mbcnt_lo_u32_b32 v0, -1, 0
	v_mbcnt_hi_u32_b32 v0, -1, v0
	s_waitcnt vmcnt(0) lgkmcnt(0)
	s_waitcnt vmcnt(0) lgkmcnt(0)
	v_add_u32_e32 v0, s84, v0
	v_cmp_gt_u32_e32 vcc, 64, v0
	s_barrier
	s_and_saveexec_b64 s[0:1], vcc
	s_cbranch_execz .LBB0_335
	s_waitcnt vmcnt(0)
	v_cmp_eq_u32_e32 vcc, 0, v0
	s_and_saveexec_b64 s[2:3], vcc
	s_cbranch_execz .LBB0_334
	s_sub_i32 s4, 7, s34
	s_getreg_b32 s5, hwreg(HW_REG_XCC_ID, 0, 4)
	s_mul_i32 s6, s98, s4
	s_lshl_b32 s5, s5, 8
	v_mov_b32_e32 v0, s5
	v_mov_b32_e32 v1, 1
	global_atomic_add v1, v0, v1, s[68:69] sc0
	s_mul_i32 s4, s101, s4
	v_mov_b32_e32 v0, 0
	s_waitcnt vmcnt(0)
	v_add_u32_e32 v1, 1, v1
	v_cmp_eq_u32_e32 vcc, s6, v1
	s_cbranch_vccz .Lgb_half_s6
	buffer_wbl2 sc1
	s_waitcnt vmcnt(0)
	v_mov_b32_e32 v1, 1
	global_atomic_add v0, v1, s[14:15]
	s_branch .Lgb_inv_s6

.LBB0_348:
	s_or_b64 exec, exec, s[2:3]
	s_cmp_lt_i32 s35, 9
	s_cbranch_scc1 .LBB0_357
	v_mbcnt_lo_u32_b32 v0, -1, 0
	v_mbcnt_hi_u32_b32 v0, -1, v0
	s_waitcnt vmcnt(0) lgkmcnt(0)
	s_waitcnt lgkmcnt(0)
	v_add_u32_e32 v0, s84, v0
	v_cmp_gt_u32_e32 vcc, 64, v0
	s_barrier
	s_and_saveexec_b64 s[0:1], vcc
	s_cbranch_execz .LBB0_356
	s_waitcnt vmcnt(0)
	s_waitcnt vmcnt(0)
	v_cmp_eq_u32_e32 vcc, 0, v0
	s_and_saveexec_b64 s[2:3], vcc
	s_cbranch_execz .LBB0_355
	s_sub_i32 s4, 8, s34
	s_getreg_b32 s5, hwreg(HW_REG_XCC_ID, 0, 4)
	s_mul_i32 s6, s98, s4
	s_lshl_b32 s5, s5, 8
	v_mov_b32_e32 v0, s5
	v_mov_b32_e32 v1, 1
	global_atomic_add v1, v0, v1, s[68:69] sc0
	s_mul_i32 s4, s101, s4
	v_mov_b32_e32 v0, 0
	s_waitcnt vmcnt(0)
	v_add_u32_e32 v1, 1, v1
	v_cmp_eq_u32_e32 vcc, s6, v1
	s_cbranch_vccz .Lgb_half_s7
	buffer_wbl2 sc1
	s_waitcnt vmcnt(0)
	v_mov_b32_e32 v1, 1
	global_atomic_add v0, v1, s[14:15]
	s_branch .Lgb_inv_s7

.LBB0_373:
	s_cmp_lt_i32 s35, 10
	s_cbranch_scc1 .LBB0_382
	v_mbcnt_lo_u32_b32 v0, -1, 0
	v_mbcnt_hi_u32_b32 v0, -1, v0
	s_waitcnt vmcnt(0) lgkmcnt(0)
	s_waitcnt vmcnt(0) lgkmcnt(0)
	v_add_u32_e32 v0, s84, v0
	v_cmp_gt_u32_e32 vcc, 64, v0
	s_barrier
	s_and_saveexec_b64 s[0:1], vcc
	s_cbranch_execz .LBB0_381
	s_waitcnt vmcnt(0)
	v_cmp_eq_u32_e32 vcc, 0, v0
	s_and_saveexec_b64 s[2:3], vcc
	s_cbranch_execz .LBB0_380
	s_sub_i32 s4, 9, s34
	s_getreg_b32 s5, hwreg(HW_REG_XCC_ID, 0, 4)
	s_mul_i32 s6, s98, s4
	s_lshl_b32 s5, s5, 8
	v_mov_b32_e32 v0, s5
	v_mov_b32_e32 v1, 1
	global_atomic_add v1, v0, v1, s[68:69] sc0
	s_mul_i32 s4, s101, s4
	v_mov_b32_e32 v0, 0
	s_waitcnt vmcnt(0)
	v_add_u32_e32 v1, 1, v1
	v_cmp_eq_u32_e32 vcc, s6, v1
	s_cbranch_vccz .Lgb_half_s8
	buffer_wbl2 sc1
	s_waitcnt vmcnt(0)
	v_mov_b32_e32 v1, 1
	global_atomic_add v0, v1, s[14:15]
	s_branch .Lgb_inv_s8

.LBB0_398:
	s_cmp_lt_i32 s35, 11
	s_cbranch_scc1 .LBB0_407
	v_mbcnt_lo_u32_b32 v0, -1, 0
	v_mbcnt_hi_u32_b32 v0, -1, v0
	s_waitcnt vmcnt(0) lgkmcnt(0)
	s_waitcnt vmcnt(0) lgkmcnt(0)
	v_add_u32_e32 v0, s84, v0
	v_cmp_gt_u32_e32 vcc, 64, v0
	s_barrier
	s_and_saveexec_b64 s[0:1], vcc
	s_cbranch_execz .LBB0_406
	s_waitcnt vmcnt(0)
	v_cmp_eq_u32_e32 vcc, 0, v0
	s_and_saveexec_b64 s[2:3], vcc
	s_cbranch_execz .LBB0_405
	s_sub_i32 s4, 10, s34
	s_getreg_b32 s5, hwreg(HW_REG_XCC_ID, 0, 4)
	s_mul_i32 s6, s98, s4
	s_lshl_b32 s5, s5, 8
	v_mov_b32_e32 v0, s5
	v_mov_b32_e32 v1, 1
	global_atomic_add v1, v0, v1, s[68:69] sc0
	s_mul_i32 s4, s101, s4
	v_mov_b32_e32 v0, 0
	s_waitcnt vmcnt(0)
	v_add_u32_e32 v1, 1, v1
	v_cmp_eq_u32_e32 vcc, s6, v1
	s_cbranch_vccz .Lgb_half_s9
	buffer_wbl2 sc1
	s_waitcnt vmcnt(0)
	v_mov_b32_e32 v1, 1
	global_atomic_add v0, v1, s[14:15]
	s_branch .Lgb_inv_s9

.LBB0_442:
	s_or_b64 exec, exec, s[0:1]
	s_cmp_lt_i32 s35, 12
	s_cbranch_scc1 .LBB0_451
	v_mbcnt_lo_u32_b32 v0, -1, 0
	v_mbcnt_hi_u32_b32 v0, -1, v0
	s_waitcnt vmcnt(0) lgkmcnt(0)
	s_waitcnt lgkmcnt(0)
	v_add_u32_e32 v0, s84, v0
	v_cmp_gt_u32_e32 vcc, 64, v0
	s_barrier
	s_and_saveexec_b64 s[0:1], vcc
	s_cbranch_execz .LBB0_450
	s_waitcnt vmcnt(0)
	s_waitcnt vmcnt(0)
	v_cmp_eq_u32_e32 vcc, 0, v0
	s_and_saveexec_b64 s[2:3], vcc
	s_cbranch_execz .LBB0_449
	s_sub_i32 s4, 11, s34
	s_getreg_b32 s5, hwreg(HW_REG_XCC_ID, 0, 4)
	s_mul_i32 s6, s98, s4
	s_lshl_b32 s5, s5, 8
	v_mov_b32_e32 v0, s5
	v_mov_b32_e32 v1, 1
	global_atomic_add v1, v0, v1, s[68:69] sc0
	s_mul_i32 s4, s101, s4
	v_mov_b32_e32 v0, 0
	s_waitcnt vmcnt(0)
	v_add_u32_e32 v1, 1, v1
	v_cmp_eq_u32_e32 vcc, s6, v1
	s_cbranch_vccz .Lgb_half_s10
	buffer_wbl2 sc1
	s_waitcnt vmcnt(0)
	v_mov_b32_e32 v1, 1
	global_atomic_add v0, v1, s[14:15]
	s_branch .Lgb_inv_s10

.LBB0_531:
	s_cmp_lt_i32 s35, 13
	s_cbranch_scc1 .LBB0_540
	v_mbcnt_lo_u32_b32 v0, -1, 0
	v_mbcnt_hi_u32_b32 v0, -1, v0
	s_waitcnt vmcnt(0) lgkmcnt(0)
	s_waitcnt vmcnt(0) lgkmcnt(0)
	v_add_u32_e32 v0, s84, v0
	v_cmp_gt_u32_e32 vcc, 64, v0
	s_barrier
	s_and_saveexec_b64 s[0:1], vcc
	s_cbranch_execz .LBB0_539
	s_waitcnt vmcnt(0)
	v_cmp_eq_u32_e32 vcc, 0, v0
	s_and_saveexec_b64 s[2:3], vcc
	s_cbranch_execz .LBB0_538
	s_sub_i32 s4, 12, s34
	s_getreg_b32 s5, hwreg(HW_REG_XCC_ID, 0, 4)
	s_mul_i32 s6, s98, s4
	s_lshl_b32 s5, s5, 8
	v_mov_b32_e32 v0, s5
	v_mov_b32_e32 v1, 1
	global_atomic_add v1, v0, v1, s[68:69] sc0
	s_mul_i32 s4, s101, s4
	v_mov_b32_e32 v0, 0
	s_waitcnt vmcnt(0)
	v_add_u32_e32 v1, 1, v1
	v_cmp_eq_u32_e32 vcc, s6, v1
	s_cbranch_vccz .Lgb_half_s11
	buffer_wbl2 sc1
	s_waitcnt vmcnt(0)
	v_mov_b32_e32 v1, 1
	global_atomic_add v0, v1, s[14:15]
	s_branch .Lgb_inv_s11

.Ldil_ret12:
.LBB0_590:
	s_cmp_lt_i32 s35, 14
	s_cbranch_scc1 .LBB0_599
	v_mbcnt_lo_u32_b32 v0, -1, 0
	v_mbcnt_hi_u32_b32 v0, -1, v0
	s_waitcnt vmcnt(0) lgkmcnt(0)
	s_waitcnt lgkmcnt(0)
	v_add_u32_e32 v0, s84, v0
	v_cmp_gt_u32_e32 vcc, 64, v0
	s_barrier
	s_and_saveexec_b64 s[0:1], vcc
	s_cbranch_execz .LBB0_598
	s_waitcnt vmcnt(0)
	s_waitcnt vmcnt(0)
	v_cmp_eq_u32_e32 vcc, 0, v0
	s_and_saveexec_b64 s[2:3], vcc
	s_cbranch_execz .LBB0_597
	s_sub_i32 s4, 13, s34
	s_getreg_b32 s5, hwreg(HW_REG_XCC_ID, 0, 4)
	s_mul_i32 s6, s98, s4
	s_lshl_b32 s5, s5, 8
	v_mov_b32_e32 v0, s5
	v_mov_b32_e32 v1, 1
	global_atomic_add v1, v0, v1, s[68:69] sc0
	s_mul_i32 s4, s101, s4
	v_mov_b32_e32 v0, 0
	s_waitcnt vmcnt(0)
	v_add_u32_e32 v1, 1, v1
	v_cmp_eq_u32_e32 vcc, s6, v1
	s_cbranch_vccz .Lgb_half_s12
	buffer_wbl2 sc1
	s_waitcnt vmcnt(0)
	v_mov_b32_e32 v1, 1
	global_atomic_add v0, v1, s[14:15]
	s_branch .Lgb_inv_s12

.LBB0_624:
	s_cmp_lt_i32 s35, 15
	s_cbranch_scc1 .LBB0_633
	v_mbcnt_lo_u32_b32 v0, -1, 0
	v_mbcnt_hi_u32_b32 v0, -1, v0
	s_waitcnt vmcnt(0) lgkmcnt(0)
	s_waitcnt vmcnt(0) lgkmcnt(0)
	v_add_u32_e32 v0, s84, v0
	v_cmp_gt_u32_e32 vcc, 64, v0
	s_barrier
	s_and_saveexec_b64 s[0:1], vcc
	s_cbranch_execz .LBB0_632
	s_waitcnt vmcnt(0)
	v_cmp_eq_u32_e32 vcc, 0, v0
	s_and_saveexec_b64 s[2:3], vcc
	s_cbranch_execz .LBB0_631
	s_sub_i32 s4, 14, s34
	s_getreg_b32 s5, hwreg(HW_REG_XCC_ID, 0, 4)
	s_mul_i32 s6, s98, s4
	s_lshl_b32 s5, s5, 8
	v_mov_b32_e32 v0, s5
	v_mov_b32_e32 v1, 1
	global_atomic_add v1, v0, v1, s[68:69] sc0
	s_mul_i32 s4, s101, s4
	v_mov_b32_e32 v0, 0
	s_waitcnt vmcnt(0)
	v_add_u32_e32 v1, 1, v1
	v_cmp_eq_u32_e32 vcc, s6, v1
	s_cbranch_vccz .Lgb_half_s13
	buffer_wbl2 sc1
	s_waitcnt vmcnt(0)
	v_mov_b32_e32 v1, 1
	global_atomic_add v0, v1, s[14:15]
	s_branch .Lgb_inv_s13

.Lmla_ret14:
.LBB0_668:
	s_cmp_lt_i32 s35, 16
	s_cbranch_scc1 .LBB0_677
	v_mbcnt_lo_u32_b32 v0, -1, 0
	v_mbcnt_hi_u32_b32 v0, -1, v0
	s_waitcnt vmcnt(0) lgkmcnt(0)
	s_waitcnt lgkmcnt(0)
	v_add_u32_e32 v0, s84, v0
	v_cmp_gt_u32_e32 vcc, 64, v0
	s_barrier
	s_and_saveexec_b64 s[0:1], vcc
	s_cbranch_execz .LBB0_676
	s_waitcnt vmcnt(0)
	s_waitcnt vmcnt(0)
	v_cmp_eq_u32_e32 vcc, 0, v0
	s_and_saveexec_b64 s[2:3], vcc
	s_cbranch_execz .LBB0_675
	s_sub_i32 s4, 15, s34
	s_getreg_b32 s5, hwreg(HW_REG_XCC_ID, 0, 4)
	s_mul_i32 s6, s98, s4
	s_lshl_b32 s5, s5, 8
	v_mov_b32_e32 v0, s5
	v_mov_b32_e32 v1, 1
	global_atomic_add v1, v0, v1, s[68:69] sc0
	s_mul_i32 s4, s101, s4
	v_mov_b32_e32 v0, 0
	s_waitcnt vmcnt(0)
	v_add_u32_e32 v1, 1, v1
	v_cmp_eq_u32_e32 vcc, s6, v1
	s_cbranch_vccz .Lgb_half_s14
	buffer_wbl2 sc1
	s_waitcnt vmcnt(0)
	v_mov_b32_e32 v1, 1
	global_atomic_add v0, v1, s[14:15]
	s_branch .Lgb_inv_s14

.LBB0_681:
	s_or_b64 exec, exec, s[2:3]
	s_cmp_lt_u32 s35, 17
	s_cbranch_scc1 .LBB0_690
	v_mbcnt_lo_u32_b32 v0, -1, 0
	v_mbcnt_hi_u32_b32 v0, -1, v0
	s_waitcnt vmcnt(0) lgkmcnt(0)
	s_waitcnt lgkmcnt(0)
	v_add_u32_e32 v0, s84, v0
	v_cmp_gt_u32_e32 vcc, 64, v0
	s_barrier
	s_and_saveexec_b64 s[0:1], vcc
	s_cbranch_execz .LBB0_689
	s_waitcnt vmcnt(0)
	s_waitcnt vmcnt(0)
	v_cmp_eq_u32_e32 vcc, 0, v0
	s_and_saveexec_b64 s[2:3], vcc
	s_cbranch_execz .LBB0_688
	s_sub_i32 s4, 16, s34
	s_getreg_b32 s5, hwreg(HW_REG_XCC_ID, 0, 4)
	s_mul_i32 s6, s98, s4
	s_lshl_b32 s5, s5, 8
	v_mov_b32_e32 v0, s5
	v_mov_b32_e32 v1, 1
	global_atomic_add v1, v0, v1, s[68:69] sc0
	s_mul_i32 s4, s101, s4
	v_mov_b32_e32 v0, 0
	s_waitcnt vmcnt(0)
	v_add_u32_e32 v1, 1, v1
	v_cmp_eq_u32_e32 vcc, s6, v1
	s_cbranch_vccz .Lgb_half_s15
	buffer_wbl2 sc1
	s_waitcnt vmcnt(0)
	v_mov_b32_e32 v1, 1
	global_atomic_add v0, v1, s[14:15]
	s_branch .Lgb_inv_s15

.LBB0_706:
	s_cmp_lt_i32 s35, 18
	s_cbranch_scc1 .LBB0_715
	v_mbcnt_lo_u32_b32 v0, -1, 0
	v_mbcnt_hi_u32_b32 v0, -1, v0
	s_waitcnt vmcnt(0) lgkmcnt(0)
	s_waitcnt vmcnt(0) lgkmcnt(0)
	v_add_u32_e32 v0, s84, v0
	v_cmp_gt_u32_e32 vcc, 64, v0
	s_barrier
	s_and_saveexec_b64 s[0:1], vcc
	s_cbranch_execz .LBB0_714
	s_waitcnt vmcnt(0)
	v_cmp_eq_u32_e32 vcc, 0, v0
	s_and_saveexec_b64 s[2:3], vcc
	s_cbranch_execz .LBB0_713
	s_sub_i32 s4, 17, s34
	s_getreg_b32 s5, hwreg(HW_REG_XCC_ID, 0, 4)
	s_mul_i32 s6, s98, s4
	s_lshl_b32 s5, s5, 8
	v_mov_b32_e32 v0, s5
	v_mov_b32_e32 v1, 1
	global_atomic_add v1, v0, v1, s[68:69] sc0
	s_mul_i32 s4, s101, s4
	v_mov_b32_e32 v0, 0
	s_waitcnt vmcnt(0)
	v_add_u32_e32 v1, 1, v1
	v_cmp_eq_u32_e32 vcc, s6, v1
	s_cbranch_vccz .Lgb_half_s16
	buffer_wbl2 sc1
	s_waitcnt vmcnt(0)
	v_mov_b32_e32 v1, 1
	global_atomic_add v0, v1, s[14:15]
	s_branch .Lgb_inv_s16

.LBB0_719:
	s_or_b64 exec, exec, s[0:1]
	s_cmp_lt_u32 s35, 19
	s_cbranch_scc1 .LBB0_728
	v_mbcnt_lo_u32_b32 v0, -1, 0
	v_mbcnt_hi_u32_b32 v0, -1, v0
	s_waitcnt vmcnt(0) lgkmcnt(0)
	s_nop 0
	v_add_u32_e32 v0, s84, v0
	v_cmp_gt_u32_e32 vcc, 64, v0
	s_barrier
	s_and_saveexec_b64 s[0:1], vcc
	s_cbranch_execz .LBB0_727
	s_waitcnt vmcnt(0)
	s_waitcnt vmcnt(0)
	v_cmp_eq_u32_e32 vcc, 0, v0
	s_and_saveexec_b64 s[2:3], vcc
	s_cbranch_execz .LBB0_726
	s_sub_i32 s4, 18, s34
	s_getreg_b32 s5, hwreg(HW_REG_XCC_ID, 0, 4)
	s_mul_i32 s6, s98, s4
	s_lshl_b32 s5, s5, 8
	v_mov_b32_e32 v0, s5
	v_mov_b32_e32 v1, 1
	global_atomic_add v1, v0, v1, s[68:69] sc0
	s_mul_i32 s4, s101, s4
	v_mov_b32_e32 v0, 0
	s_waitcnt vmcnt(0)
	v_add_u32_e32 v1, 1, v1
	v_cmp_eq_u32_e32 vcc, s6, v1
	s_cbranch_vccz .Lgb_half_s17
	buffer_wbl2 sc1
	s_waitcnt vmcnt(0)
	v_mov_b32_e32 v1, 1
	global_atomic_add v0, v1, s[14:15]
	s_branch .Lgb_inv_s17

.LBB0_744:
	s_cmp_lt_i32 s35, 20
	s_cbranch_scc1 .LBB0_753
	v_mbcnt_lo_u32_b32 v0, -1, 0
	v_mbcnt_hi_u32_b32 v0, -1, v0
	s_waitcnt vmcnt(0) lgkmcnt(0)
	s_waitcnt vmcnt(0) lgkmcnt(0)
	v_add_u32_e32 v0, s84, v0
	v_cmp_gt_u32_e32 vcc, 64, v0
	s_barrier
	s_and_saveexec_b64 s[0:1], vcc
	s_cbranch_execz .LBB0_752
	s_waitcnt vmcnt(0)
	v_cmp_eq_u32_e32 vcc, 0, v0
	s_and_saveexec_b64 s[2:3], vcc
	s_cbranch_execz .LBB0_751
	s_sub_i32 s4, 19, s34
	s_getreg_b32 s5, hwreg(HW_REG_XCC_ID, 0, 4)
	s_mul_i32 s6, s98, s4
	s_lshl_b32 s5, s5, 8
	v_mov_b32_e32 v0, s5
	v_mov_b32_e32 v1, 1
	global_atomic_add v1, v0, v1, s[68:69] sc0
	s_mul_i32 s4, s101, s4
	v_mov_b32_e32 v0, 0
	s_waitcnt vmcnt(0)
	v_add_u32_e32 v1, 1, v1
	v_cmp_eq_u32_e32 vcc, s6, v1
	s_cbranch_vccz .Lgb_half_s18
	buffer_wbl2 sc1
	s_waitcnt vmcnt(0)
	v_mov_b32_e32 v1, 1
	global_atomic_add v0, v1, s[14:15]
	s_branch .Lgb_inv_s18

.LBB0_769:
	s_cmp_lt_i32 s35, 21
	s_cbranch_scc1 .LBB0_778
	v_mbcnt_lo_u32_b32 v0, -1, 0
	v_mbcnt_hi_u32_b32 v0, -1, v0
	s_waitcnt vmcnt(0) lgkmcnt(0)
	s_waitcnt vmcnt(0) lgkmcnt(0)
	v_add_u32_e32 v0, s84, v0
	v_cmp_gt_u32_e32 vcc, 64, v0
	s_barrier
	s_and_saveexec_b64 s[0:1], vcc
	s_cbranch_execz .LBB0_777
	s_waitcnt vmcnt(0)
	v_cmp_eq_u32_e32 vcc, 0, v0
	s_and_saveexec_b64 s[2:3], vcc
	s_cbranch_execz .LBB0_776
	s_sub_i32 s4, 20, s34
	s_getreg_b32 s5, hwreg(HW_REG_XCC_ID, 0, 4)
	s_mul_i32 s6, s98, s4
	s_lshl_b32 s5, s5, 8
	v_mov_b32_e32 v0, s5
	v_mov_b32_e32 v1, 1
	global_atomic_add v1, v0, v1, s[68:69] sc0
	s_mul_i32 s4, s101, s4
	v_mov_b32_e32 v0, 0
	s_waitcnt vmcnt(0)
	v_add_u32_e32 v1, 1, v1
	v_cmp_eq_u32_e32 vcc, s6, v1
	s_cbranch_vccz .Lgb_half_s19
	buffer_wbl2 sc1
	s_waitcnt vmcnt(0)
	v_mov_b32_e32 v1, 1
	global_atomic_add v0, v1, s[14:15]
	s_branch .Lgb_inv_s19

.LBB0_782:
	s_or_b64 exec, exec, s[0:1]
	s_cmp_lt_u32 s35, 22
	s_cbranch_scc1 .LBB0_791
	v_mbcnt_lo_u32_b32 v0, -1, 0
	v_mbcnt_hi_u32_b32 v0, -1, v0
	s_waitcnt vmcnt(0) lgkmcnt(0)
	s_waitcnt lgkmcnt(0)
	v_add_u32_e32 v0, s84, v0
	v_cmp_gt_u32_e32 vcc, 64, v0
	s_barrier
	s_and_saveexec_b64 s[0:1], vcc
	s_cbranch_execz .LBB0_790
	s_waitcnt vmcnt(0)
	s_waitcnt vmcnt(0)
	v_cmp_eq_u32_e32 vcc, 0, v0
	s_and_saveexec_b64 s[2:3], vcc
	s_cbranch_execz .LBB0_789
	s_sub_i32 s4, 21, s34
	s_getreg_b32 s5, hwreg(HW_REG_XCC_ID, 0, 4)
	s_mul_i32 s6, s98, s4
	s_lshl_b32 s5, s5, 8
	v_mov_b32_e32 v0, s5
	v_mov_b32_e32 v1, 1
	global_atomic_add v1, v0, v1, s[68:69] sc0
	s_mul_i32 s4, s101, s4
	v_mov_b32_e32 v0, 0
	s_waitcnt vmcnt(0)
	v_add_u32_e32 v1, 1, v1
	v_cmp_eq_u32_e32 vcc, s6, v1
	s_cbranch_vccz .Lgb_half_s20
	buffer_wbl2 sc1
	s_waitcnt vmcnt(0)
	v_mov_b32_e32 v1, 1
	global_atomic_add v0, v1, s[14:15]
	s_branch .Lgb_inv_s20
